# pass1 state-update K-fragment LDS reads software-pipelined (ping-pong buffers, counted lgkmcnt)
# speedup vs baseline: 1.0324x; 1.0104x over previous
; #define LAS __attribute__((address_space(3)))
; #define MFMA32(a, b, c) __builtin_amdgcn_mfma_f32_32x32x16_bf16((a), (b), (c), 0, 0, 0)
; __device__ __forceinline__ void mlstm_pass1(const bf16_t* PR, const bf16_t* QC, const bf16_t* KC, const float* Gt, const float* gain, bf16_t* Y, LAS unsigned char* lds, ...
;     ...
;                 bf16x8 vwf[4];
;                 { const LAS unsigned char* vb = vwb + (8 * h + (li >> 2)) * vstr + (16 * gg + 4 * (li & 3)) * 2;
; #pragma unroll
;                   for (int sp = 0; sp < 4; ++sp) vwf[sp] = tr2(vb + (16 * sp) * vstr, vb + (16 * sp + 4) * vstr); }
; #pragma unroll
;                 for (int i = 0; i < 4; ++i) {
; #pragma unroll
;                     for (int e = 0; e < 16; ++e) C[i][e] *= decay;
;                     const LAS unsigned char* kb = lds + ML_KT + (8 * h + (li >> 2)) * KROW + (32 * i + 16 * gg + 4 * (li & 3)) * 2;
; #pragma unroll
;                     for (int sp = 0; sp < 4; ++sp) C[i] = MFMA32(tr2(kb + (16 * sp) * KROW, kb + (16 * sp + 4) * KROW), vwf[sp], C[i]);
;                 }
.LBB0_480:
	v_mul_f32_e32 v64, s74, v163
	v_exp_f32_e32 v80, v64
	v_add_u32_e32 v64, s84, v169
	v_add_u32_e32 v66, s87, v169
	ds_read_b64_tr_b16 v[78:79], v64
	ds_read_b64_tr_b16 v[66:67], v66
	v_add_u32_e32 v64, s73, v169
	ds_read_b64_tr_b16 v[76:77], v169
	ds_read_b64_tr_b16 v[72:73], v64
	v_add_u32_e32 v64, s85, v169
	ds_read_b64_tr_b16 v[74:75], v64
	v_add_u32_e32 v64, s5, v169
	ds_read_b64_tr_b16 v[68:69], v64
	v_add_u32_e32 v64, s86, v169
	ds_read_b64_tr_b16 v[70:71], v64
	v_add_u32_e32 v64, s7, v169
	ds_read_b64_tr_b16 v[64:65], v64
	ds_read_b64_tr_b16 v[82:83], v181
	ds_read_b64_tr_b16 v[84:85], v181 offset:1088
	v_pk_mul_f32 v[46:47], v[46:47], v[80:81] op_sel_hi:[1,0]
	v_pk_mul_f32 v[44:45], v[44:45], v[80:81] op_sel_hi:[1,0]
	v_pk_mul_f32 v[42:43], v[42:43], v[80:81] op_sel_hi:[1,0]
	v_pk_mul_f32 v[40:41], v[40:41], v[80:81] op_sel_hi:[1,0]
	v_pk_mul_f32 v[38:39], v[38:39], v[80:81] op_sel_hi:[1,0]
	v_pk_mul_f32 v[36:37], v[36:37], v[80:81] op_sel_hi:[1,0]
	v_pk_mul_f32 v[34:35], v[34:35], v[80:81] op_sel_hi:[1,0]
	v_pk_mul_f32 v[32:33], v[32:33], v[80:81] op_sel_hi:[1,0]
	v_pk_mul_f32 v[62:63], v[62:63], v[80:81] op_sel_hi:[1,0]
	v_pk_mul_f32 v[60:61], v[60:61], v[80:81] op_sel_hi:[1,0]
	ds_read_b64_tr_b16 v[208:209], v181 offset:4352
	ds_read_b64_tr_b16 v[210:211], v181 offset:5440
	s_waitcnt lgkmcnt(2)
	v_mfma_f32_32x32x16_bf16 v[32:47], v[82:85], v[76:79], v[32:47]
	v_mul_f32_e64 v58, v58, v80
	v_mul_f32_e64 v59, v59, v80
	v_mul_f32_e64 v56, v56, v80
	v_mul_f32_e64 v57, v57, v80
	v_pk_mul_f32 v[54:55], v[54:55], v[80:81] op_sel_hi:[1,0]
	v_pk_mul_f32 v[52:53], v[52:53], v[80:81] op_sel_hi:[1,0]
	v_pk_mul_f32 v[50:51], v[50:51], v[80:81] op_sel_hi:[1,0]
	v_pk_mul_f32 v[48:49], v[48:49], v[80:81] op_sel_hi:[1,0]
	ds_read_b64_tr_b16 v[82:83], v181 offset:8704
	ds_read_b64_tr_b16 v[84:85], v181 offset:9792
	s_waitcnt lgkmcnt(2)
	v_mfma_f32_32x32x16_bf16 v[32:47], v[208:211], v[72:75], v[32:47]
	v_mul_f32_e64 v30, v30, v80
	v_mul_f32_e64 v31, v31, v80
	v_mul_f32_e64 v28, v28, v80
	v_mul_f32_e64 v29, v29, v80
	v_pk_mul_f32 v[26:27], v[26:27], v[80:81] op_sel_hi:[1,0]
	v_pk_mul_f32 v[24:25], v[24:25], v[80:81] op_sel_hi:[1,0]
	v_pk_mul_f32 v[22:23], v[22:23], v[80:81] op_sel_hi:[1,0]
	v_pk_mul_f32 v[20:21], v[20:21], v[80:81] op_sel_hi:[1,0]
	ds_read_b64_tr_b16 v[208:209], v181 offset:13056
	ds_read_b64_tr_b16 v[210:211], v181 offset:14144
	s_waitcnt lgkmcnt(2)
	v_mfma_f32_32x32x16_bf16 v[32:47], v[82:85], v[68:71], v[32:47]
	v_mul_f32_e64 v18, v18, v80
	v_mul_f32_e64 v19, v19, v80
	v_mul_f32_e64 v16, v16, v80
	v_mul_f32_e64 v17, v17, v80
	v_pk_mul_f32 v[14:15], v[14:15], v[80:81] op_sel_hi:[1,0]
	v_pk_mul_f32 v[12:13], v[12:13], v[80:81] op_sel_hi:[1,0]
	v_pk_mul_f32 v[10:11], v[10:11], v[80:81] op_sel_hi:[1,0]
	v_pk_mul_f32 v[8:9], v[8:9], v[80:81] op_sel_hi:[1,0]
	ds_read_b64_tr_b16 v[82:83], v181 offset:64
	ds_read_b64_tr_b16 v[84:85], v181 offset:1152
	s_waitcnt lgkmcnt(2)
	v_mfma_f32_32x32x16_bf16 v[32:47], v[208:211], v[64:67], v[32:47]
	v_mul_f32_e64 v6, v6, v80
	v_mul_f32_e64 v7, v7, v80
	v_mul_f32_e64 v4, v4, v80
	v_mul_f32_e64 v5, v5, v80
	v_pk_mul_f32 v[2:3], v[2:3], v[80:81] op_sel_hi:[1,0]
	v_pk_mul_f32 v[0:1], v[0:1], v[80:81] op_sel_hi:[1,0]
	s_mov_b32 s94, s78
	s_mov_b32 s95, 0x66666667
	ds_read_b64_tr_b16 v[208:209], v181 offset:4416
	ds_read_b64_tr_b16 v[210:211], v181 offset:5504
	s_waitcnt lgkmcnt(2)
	v_mfma_f32_32x32x16_bf16 v[48:63], v[82:85], v[76:79], v[48:63]
	ds_read_b64_tr_b16 v[82:83], v181 offset:8768
	ds_read_b64_tr_b16 v[84:85], v181 offset:9856
	s_waitcnt lgkmcnt(2)
	v_mfma_f32_32x32x16_bf16 v[48:63], v[208:211], v[72:75], v[48:63]
	ds_read_b64_tr_b16 v[208:209], v181 offset:13120
	ds_read_b64_tr_b16 v[210:211], v181 offset:14208
	s_waitcnt lgkmcnt(2)
	v_mfma_f32_32x32x16_bf16 v[48:63], v[82:85], v[68:71], v[48:63]
	ds_read_b64_tr_b16 v[82:83], v181 offset:128
	ds_read_b64_tr_b16 v[84:85], v181 offset:1216
	s_waitcnt lgkmcnt(2)
	v_mfma_f32_32x32x16_bf16 v[48:63], v[208:211], v[64:67], v[48:63]
	ds_read_b64_tr_b16 v[208:209], v181 offset:4480
	ds_read_b64_tr_b16 v[210:211], v181 offset:5568
	s_waitcnt lgkmcnt(2)
	v_mfma_f32_32x32x16_bf16 v[16:31], v[82:85], v[76:79], v[16:31]
	ds_read_b64_tr_b16 v[82:83], v181 offset:8832
	ds_read_b64_tr_b16 v[84:85], v181 offset:9920
	s_waitcnt lgkmcnt(2)
	v_mfma_f32_32x32x16_bf16 v[16:31], v[208:211], v[72:75], v[16:31]
	ds_read_b64_tr_b16 v[208:209], v181 offset:13184
	ds_read_b64_tr_b16 v[210:211], v181 offset:14272
	s_waitcnt lgkmcnt(2)
	v_mfma_f32_32x32x16_bf16 v[16:31], v[82:85], v[68:71], v[16:31]
	ds_read_b64_tr_b16 v[82:83], v181 offset:192
	ds_read_b64_tr_b16 v[84:85], v181 offset:1280
	s_waitcnt lgkmcnt(2)
	v_mfma_f32_32x32x16_bf16 v[16:31], v[208:211], v[64:67], v[16:31]
	ds_read_b64_tr_b16 v[208:209], v181 offset:4544
	ds_read_b64_tr_b16 v[210:211], v181 offset:5632
	s_waitcnt lgkmcnt(2)
	v_mfma_f32_32x32x16_bf16 v[0:15], v[82:85], v[76:79], v[0:15]
	ds_read_b64_tr_b16 v[82:83], v181 offset:8896
	ds_read_b64_tr_b16 v[84:85], v181 offset:9984
	s_waitcnt lgkmcnt(2)
	v_mfma_f32_32x32x16_bf16 v[0:15], v[208:211], v[72:75], v[0:15]
	ds_read_b64_tr_b16 v[208:209], v181 offset:13248
	ds_read_b64_tr_b16 v[210:211], v181 offset:14336
	s_waitcnt lgkmcnt(2)
	v_mfma_f32_32x32x16_bf16 v[0:15], v[82:85], v[68:71], v[0:15]
	s_waitcnt lgkmcnt(0)
	v_mfma_f32_32x32x16_bf16 v[0:15], v[208:211], v[64:67], v[0:15]
